# attnA loop: QK-B and PV MFMAs interleaved into the softmax VALU stream (same math/order)
# speedup vs baseline: 1.1443x; 1.0149x over previous
; DI int ltid_w(int wave) { int t; asm volatile("v_mbcnt_lo_u32_b32 %0, -1, 0\n\tv_mbcnt_hi_u32_b32 %0, -1, %0" : "=v"(t)); return (wave << 6) | t; }
; template <int MODE>
; DI void attn_mfma(const Params& p, int l, int b, int hd, int qb, unsigned char* smem) {
;     ...
;   const int tid = ltid_w(p.wave), lane = tid & 63, wv = tid >> 6, r = lane & 31, h2 = lane >> 5;
;   const int mp = MODE ? 0 : (wv >> 1);
;   const bf16_t* P = (const bf16_t*)(p.ws + WS_P);
;   bf16_t* MIX = (bf16_t*)(p.ws + WS_HM);
;   const int kvh = MODE ? (hd >> 1) : hd;
;   const bf16_t* VT = MODE ? (const bf16_t*)(p.ws + WS_VTC) + ((size_t)(b * 2 + kvh) * 64) * NTOK : (const bf16_t*)(p.ws + WS_VTA) + ((size_t)(b * 4 + hd) * 64) * NTOK;
;   const int qcol = MODE ? C_Q + hd * 64 : A_Q + hd * 64;
;   const int kcol = MODE ? C_K + kvh * 64 : A_K + hd * 64;
;   unsigned char* sK = smem;
;   unsigned char* sV = smem + 8192;
;   const int tq = qb * QPB + (MODE ? wv : (wv & 1)) * 32 + r;
;   const size_t qrow = (size_t)b * NTOK + tq;
;   bf16x8 qf[KS];
; #pragma unroll
;   for (int ks = 0; ks < KS; ++ks) qf[ks] = *(const bf16x8*)(P + qrow * PW + qcol + (2 * (mp * 2 + ks) + h2) * 8);
;   const bool isctx = qb * QPB < NCTX;
;   int ntiles, band_lo = 0;
;   if (MODE == 0) ntiles = isctx ? 4 : 36;
;   else {
;     if (isctx) ntiles = 4;
;     else { const int i0 = qb * QPB - NCTX; int lo = i0 - 128; if (lo < 0) lo = 0; int hi = i0 + 256; if (hi > NLAT) hi = NLAT; band_lo = lo; ntiles = 4 + (hi - lo) / 64; }
;   }
;   const float cexp = (MODE ? 0.125f : 0.17677669529663687f) * 1.4426950408889634f;
;   float mrun = MODE ? p.sw_sink[l * 4 + hd] * 1.4426950408889634f : -1e30f;
;   float lsum = (MODE && h2 == 0) ? 1.f : 0.f;
;   f32x16 O[2];
; #pragma unroll
;   for (int vt = 0; vt < 2; ++vt)
; #pragma unroll
;     for (int i = 0; i < 16; ++i) O[vt][i] = 0.f;
;   const int lrow = tid >> 3, lc = tid & 7;
;   auto tile_base = [&](int j) -> int { return (MODE == 0 || j < 4) ? j * 64 : NCTX + band_lo + (j - 4) * 64; };
;   uint4 gk00, gk01, gk10, gk11, gv00, gv01, gv10, gv11;
;     ...
;   ATT_LOAD(tile_base(0), gk00, gk01, gv00, gv01);
;   ATT_LOAD(tile_base(1), gk10, gk11, gv10, gv11);
.LBB0_575:
	s_andn2_b64 vcc, exec, s[0:1]
	s_cbranch_vccnz .LBB0_591
	s_add_i32 s0, s46, 0xffc0
	s_and_b32 s8, s0, 0xffff
	s_mul_i32 s1, s8, 0xe38f
	s_lshr_b32 s5, s1, 21
	s_mul_i32 s1, s5, 36
	s_sub_i32 s2, s0, s1
	s_and_b32 s0, s2, 0xffff
	s_cmp_lt_u32 s0, 4
	v_readlane_b32 s6, v254, 12
	s_cselect_b64 s[0:1], -1, 0
	v_readlane_b32 s7, v254, 13
	s_and_b64 s[6:7], s[6:7], s[0:1]
	s_and_b64 vcc, exec, s[6:7]
	s_cbranch_vccnz .LBB0_591
	s_and_b32 s4, 0xffff, s5
	s_lshr_b32 s9, s4, 2
	s_and_b32 s6, s4, 3
	v_readlane_b32 s4, v253, 39
	s_add_u32 s10, s40, 0x41c6000
	v_mbcnt_lo_u32_b32 v6, -1, 0
	v_mbcnt_hi_u32_b32 v6, -1, v6
	s_addc_u32 s11, s41, 0
	v_or_b32_e32 v196, s4, v6
	s_lshl_b32 s4, s9, 8
	s_lshl_b32 s7, s6, 6
	s_or_b32 s4, s7, s4
	s_mulk_i32 s4, 0x1200
	s_add_u32 s4, s40, s4
	s_addc_u32 s13, s41, 0
	s_add_u32 s12, s4, 0xef06000
	s_addc_u32 s13, s13, 0
	s_lshl_b32 s2, s2, 6
	s_and_b32 s2, s2, 0xffc0
	v_lshrrev_b32_e32 v0, 1, v196
	s_mul_i32 s14, s9, 0x900
	v_and_b32_e32 v198, 31, v6
	v_and_b32_e32 v199, 32, v0
	s_add_i32 s2, s14, s2
	v_bfe_u32 v171, v6, 5, 1
	v_or3_b32 v165, v198, s2, v199
	v_ashrrev_i32_e32 v197, 7, v196
	v_mul_lo_u32 v160, v165, s33
	v_lshlrev_b32_e32 v164, 3, v171
	v_lshl_add_u64 v[166:167], s[10:11], 0, v[160:161]
	s_lshl_b32 s2, s6, 7
	v_lshl_or_b32 v2, v197, 5, v164
	v_lshl_add_u64 v[0:1], v[166:167], 0, s[2:3]
	v_ashrrev_i32_e32 v3, 31, v2
	v_lshl_add_u64 v[0:1], v[2:3], 1, v[0:1]
	v_ashrrev_i32_e32 v8, 3, v196
	s_waitcnt vmcnt(0)
	global_load_dwordx4 v[96:99], v[0:1], off
	global_load_dwordx4 v[100:103], v[0:1], off offset:32
	v_add_u32_e32 v7, s14, v8
	v_mov_b64_e32 v[0:1], s[10:11]
	v_lshlrev_b32_e32 v9, 4, v6
	s_and_b64 s[0:1], s[0:1], exec
	v_mad_i64_i32 v[2:3], s[0:1], v7, s33, v[0:1]
	v_and_b32_e32 v160, 0x70, v9
	s_cselect_b32 s4, 4, 36
	v_lshl_add_u64 v[4:5], v[2:3], 0, s[2:3]
	v_lshl_add_u64 v[2:3], v[2:3], 0, v[160:161]
	s_or_b32 s0, s2, 0x200
	s_mov_b32 s1, s3
	v_lshl_add_u64 v[2:3], v[2:3], 0, s[0:1]
	s_mov_b32 s14, 0x44000
	v_add_co_u32_e32 v2, vcc, s14, v2
	v_lshl_add_u64 v[4:5], v[4:5], 0, v[160:161]
	s_nop 0
	v_addc_co_u32_e32 v3, vcc, 0, v3, vcc
	global_load_dwordx4 v[104:107], v[4:5], off offset:512
	global_load_dwordx4 v[108:111], v[2:3], off offset:1024
	v_mov_b64_e32 v[2:3], s[12:13]
	v_add_u32_e32 v6, 32, v8
	v_mad_i64_i32 v[4:5], s[10:11], v8, s67, v[2:3]
	v_mad_i64_i32 v[2:3], s[10:11], v6, s67, v[2:3]
	v_add_u32_e32 v6, 64, v7
	v_mad_i64_i32 v[0:1], s[10:11], v6, s33, v[0:1]
	v_lshl_add_u64 v[6:7], v[0:1], 0, s[2:3]
	v_lshl_add_u64 v[0:1], v[0:1], 0, v[160:161]
	v_lshl_add_u64 v[0:1], v[0:1], 0, s[0:1]
	v_lshl_add_u64 v[6:7], v[6:7], 0, v[160:161]
	v_add_co_u32_e32 v0, vcc, s14, v0
	v_lshl_add_u64 v[4:5], v[4:5], 0, v[160:161]
	v_lshl_add_u64 v[2:3], v[2:3], 0, v[160:161]
	v_addc_co_u32_e32 v1, vcc, 0, v1, vcc
	global_load_dwordx4 v[112:115], v[6:7], off offset:512
	global_load_dwordx4 v[116:119], v[0:1], off offset:1024
	global_load_dwordx4 v[120:123], v[4:5], off
	global_load_dwordx4 v[124:127], v[4:5], off offset:128
	global_load_dwordx4 v[128:131], v[2:3], off
	global_load_dwordx4 v[132:135], v[2:3], off offset:128
	s_movk_i32 s0, 0x70
	v_bitop3_b32 v0, v196, s0, v9 bitop3:0x48
	s_movk_i32 s0, 0x88
	v_mul_lo_u32 v2, v8, s0
	s_mul_i32 s0, s9, 0x90000
	s_mul_i32 s1, s6, 0x24000
	s_add_i32 s0, s0, s1
	v_lshlrev_b32_e32 v1, 2, v197
	v_bfe_u32 v4, v196, 1, 3
	s_lshl_b32 s0, s0, 1
	v_lshl_or_b32 v141, v8, 7, v0
	v_lshlrev_b32_e32 v0, 7, v198
	v_or_b32_e32 v3, v1, v171
	v_bitop3_b32 v1, v1, v4, v171 bitop3:0x36
	s_add_u32 s0, s40, s0
	v_lshl_add_u32 v142, v1, 4, v0
	v_bitop3_b32 v1, v3, v4, 2 bitop3:0x36
	s_addc_u32 s1, s41, 0
	v_lshl_add_u32 v143, v1, 4, v0
	v_mov_b64_e32 v[0:1], s[0:1]
	s_and_b32 s5, s5, 3
	v_mbcnt_hi_u32_b32 v5, -1, v185
	v_mad_i64_i32 v[136:137], s[0:1], v8, s67, v[0:1]
	s_lshl_b32 s5, s5, 7
	v_and_b32_e32 v7, 64, v5
	s_mul_hi_u32 s0, s8, 0x1c71c72
	s_add_u32 s5, s40, s5
	v_xor_b32_e32 v6, 32, v5
	v_add_u32_e32 v7, 64, v7
	s_mul_hi_u32 s1, s0, 0x1332000
	s_mul_i32 s0, s0, 0x1332000
	s_addc_u32 s8, s41, 0
	v_cmp_lt_i32_e32 vcc, v6, v7
	s_add_u32 s0, s5, s0
	s_addc_u32 s1, s8, s1
	v_cndmask_b32_e32 v5, v5, v6, vcc
	v_lshlrev_b32_e32 v170, 2, v5
	v_mul_u32_u24_e32 v5, 0x88, v198
	v_mov_b64_e32 v[0:1], s[0:1]
	v_mov_b32_e32 v200, 0
	s_mov_b32 s2, 0
	v_mad_i64_i32 v[138:139], s[0:1], v8, s33, v[0:1]
	v_mov_b32_e32 v140, 0xf149f2ca
	v_add_u32_e32 v144, v2, v160
	v_add_u32_e32 v145, v164, v5
	v_add_u32_e32 v236, 0x2000, v145
	v_add_u32_e32 v237, 0x3000, v145
	v_add_u32_e32 v238, 0x6000, v145
	v_add_u32_e32 v239, 0x7000, v145
	v_mov_b32_e32 v16, 0
	v_mov_b32_e32 v17, v200
	v_mov_b32_e32 v18, v200
	v_mov_b32_e32 v19, v200
	v_mov_b32_e32 v20, v200
	v_mov_b32_e32 v21, v200
	v_mov_b32_e32 v22, v200
	v_mov_b32_e32 v23, v200
	v_mov_b32_e32 v24, v200
	v_mov_b32_e32 v25, v200
	v_mov_b32_e32 v26, v200
	v_mov_b32_e32 v27, v200
	v_mov_b32_e32 v28, v200
	v_mov_b32_e32 v29, v200
	v_mov_b32_e32 v30, v200
	v_mov_b32_e32 v31, v200
	v_mov_b32_e32 v0, v200
	v_mov_b32_e32 v1, v200
	v_mov_b32_e32 v2, v200
	v_mov_b32_e32 v3, v200
	v_mov_b32_e32 v4, v200
	v_mov_b32_e32 v5, v200
	v_mov_b32_e32 v6, v200
	v_mov_b32_e32 v7, v200
	v_mov_b32_e32 v8, v200
	v_mov_b32_e32 v9, v200
	v_mov_b32_e32 v10, v200
	v_mov_b32_e32 v11, v200
	v_mov_b32_e32 v12, v200
	v_mov_b32_e32 v13, v200
	v_mov_b32_e32 v14, v200
	v_mov_b32_e32 v15, v200
	s_branch .LBB0_580
; #define MFMA32(a, b, c) __builtin_amdgcn_mfma_f32_32x32x16_bf16((a), (b), (c), 0, 0, 0)
; DI int crow(int reg, int h) { return (reg & 3) + 8 * (reg >> 2) + 4 * h; }
; template <int MODE>
; DI void attn_mfma(const Params& p, int l, int b, int hd, int qb, unsigned char* smem) {
;     ...
;   for (int j = 0; j < ntiles; j += 2) {
;     __syncthreads();
;     ATT_STORE(0, gk00, gk01, gv00, gv01);
;     ATT_STORE(1, gk10, gk11, gv10, gv11);
;     __syncthreads();
;     if (j + 2 < ntiles) {
;       ATT_LOAD(tile_base(j + 2), gk00, gk01, gv00, gv01);
;       ATT_LOAD(tile_base(j + 3), gk10, gk11, gv10, gv11);
;     }
;     f32x16 SA0, SA1, SB0, SB1;
; #pragma unroll
;     for (int i = 0; i < 16; ++i) { SA0[i] = 0.f; SA1[i] = 0.f; SB0[i] = 0.f; SB1[i] = 0.f; }
; #pragma unroll
;     for (int ks = 0; ks < KS; ++ks) {
;       const int kk = mp * 2 + ks;
;       const int key0 = r, key1 = 32 + r;
;       const int o0 = key0 * 128 + (((2 * kk + h2) ^ ((key0 >> 1) & 7)) << 4), o1 = key1 * 128 + (((2 * kk + h2) ^ ((key1 >> 1) & 7)) << 4);
;       SA0 = MFMA32(*(const bf16x8*)(sK + o0), qf[ks], SA0);
;       SA1 = MFMA32(*(const bf16x8*)(sK + o1), qf[ks], SA1);
;       SB0 = MFMA32(*(const bf16x8*)(sK + 16896 + o0), qf[ks], SB0);
;       SB1 = MFMA32(*(const bf16x8*)(sK + 16896 + o1), qf[ks], SB1);
;     }
; #pragma unroll
;     for (int hf = 0; hf < 2; ++hf) {
;     const unsigned char* sVc = sV + hf * 16896;
;     const int tbcur = tile_base(j + hf);
;     f32x16 S[2];
;     S[0] = hf == 0 ? SA0 : SB0;
;     S[1] = hf == 0 ? SA1 : SB1;
;     if (MODE == 1 && j + hf >= 4) {
;       const int iq = tq - NCTX;
;       const int jb = tbcur - NCTX;
; #pragma unroll
;       for (int mt = 0; mt < 2; ++mt)
; #pragma unroll
;         for (int i = 0; i < 16; ++i) {
;           const int dd = iq - (jb + mt * 32 + crow(i, h2));
;           if (dd > 128 || dd < -128) S[mt][i] = -1e30f;
;         }
;     }
;     float mx = -1e30f;
; #pragma unroll
;     for (int mt = 0; mt < 2; ++mt)
; #pragma unroll
;       for (int i = 0; i < 16; ++i) mx = fmaxf(mx, S[mt][i]);
;     mx = fmaxf(mx, __shfl_xor(mx, 32));
;     const float zmx = mx * cexp;
;     if (__any(zmx > mrun + 8.f)) {
;       const float mnew = fmaxf(mrun, zmx);
;       const float alpha = __builtin_amdgcn_exp2f(mrun - mnew);
.LBB0_580:
	v_add_u32_e32 v32, 0x2000, v144
	s_add_i32 s2, s2, 2
	s_waitcnt lgkmcnt(0)
	s_barrier
	s_waitcnt vmcnt(0)
	ds_write_b128 v141, v[104:107]
	ds_write_b128 v141, v[108:111] offset:4096
	ds_write2_b64 v32, v[120:121], v[122:123] offset1:1
	v_add_u32_e32 v32, 0x3100, v144
	s_cmp_ge_u32 s2, s4
	ds_write2_b64 v32, v[128:129], v[130:131] offset1:1
	ds_write_b128 v141, v[112:115] offset:16896
	ds_write_b128 v141, v[116:119] offset:20992
	v_add_u32_e32 v32, 0x6200, v144
	s_cselect_b64 s[0:1], -1, 0
	ds_write2_b64 v32, v[124:125], v[126:127] offset1:1
	v_add_u32_e32 v32, 0x7300, v144
	s_and_b64 vcc, exec, s[0:1]
	ds_write2_b64 v32, v[132:133], v[134:135] offset1:1
	s_waitcnt lgkmcnt(0)
	s_barrier
	ds_read_b128 v[204:207], v142
	ds_read_b128 v[208:211], v143
	ds_read_b128 v[212:215], v142 offset:4096
	ds_read_b128 v[216:219], v143 offset:4096
	ds_read_b128 v[220:223], v142 offset:16896
	ds_read_b128 v[224:227], v143 offset:16896
	ds_read_b128 v[228:231], v142 offset:20992
	ds_read_b128 v[232:235], v143 offset:20992
	s_cbranch_vccnz .LBB0_582
	v_lshl_add_u64 v[32:33], v[138:139], 0, v[160:161]
	v_add_co_u32_e32 v34, vcc, 0x42d7000, v32
	s_nop 1
	v_addc_co_u32_e32 v35, vcc, 0, v33, vcc
	v_add_co_u32_e32 v36, vcc, 0x431b000, v32
	s_nop 1
	v_addc_co_u32_e32 v37, vcc, 0, v33, vcc
	global_load_dwordx4 v[104:107], v[34:35], off offset:512
	global_load_dwordx4 v[108:111], v[36:37], off offset:1536
	v_lshl_add_u64 v[34:35], v[136:137], 0, v[160:161]
	v_add_co_u32_e32 v36, vcc, 0xef06000, v34
	s_nop 1
	v_addc_co_u32_e32 v37, vcc, 0, v35, vcc
	v_add_co_u32_e32 v34, vcc, 0xef2a000, v34
	s_nop 1
	v_addc_co_u32_e32 v35, vcc, 0, v35, vcc
	v_add_co_u32_e32 v38, vcc, 0x435f000, v32
	s_nop 1
	v_addc_co_u32_e32 v39, vcc, 0, v33, vcc
	v_add_co_u32_e32 v32, vcc, 0x43a3000, v32
	s_nop 1
	v_addc_co_u32_e32 v33, vcc, 0, v33, vcc
	global_load_dwordx4 v[112:115], v[38:39], off offset:2560
	global_load_dwordx4 v[116:119], v[32:33], off offset:3584
	global_load_dwordx4 v[120:123], v[36:37], off offset:256
	global_load_dwordx4 v[124:127], v[36:37], off offset:384
	global_load_dwordx4 v[128:131], v[34:35], off offset:256
	global_load_dwordx4 v[132:135], v[34:35], off offset:384
.LBB0_582:
	s_mov_b32 s5, 0xf149f2ca
	s_mov_b32 s8, 0x3e8293ee
	s_waitcnt lgkmcnt(6)
	v_mfma_f32_32x32x16_bf16 v[80:95], v[204:207], v[96:99], 0
	v_mfma_f32_32x32x16_bf16 v[80:95], v[208:211], v[100:103], v[80:95]
	s_waitcnt lgkmcnt(4)
	v_mfma_f32_32x32x16_bf16 v[64:79], v[212:215], v[96:99], 0
	v_mfma_f32_32x32x16_bf16 v[64:79], v[216:219], v[100:103], v[64:79]
	s_waitcnt lgkmcnt(0)
	v_mfma_f32_32x32x16_bf16 v[48:63], v[220:223], v[96:99], 0
	ds_read2_b64 v[204:207], v236 offset1:2
	ds_read2_b64 v[208:211], v237 offset0:32 offset1:34
	ds_read2_b64 v[212:215], v236 offset0:4 offset1:6
	ds_read2_b64 v[216:219], v237 offset0:36 offset1:38
	v_mfma_f32_32x32x16_bf16 v[48:63], v[224:227], v[100:103], v[48:63]
	s_nop 1
	v_max3_f32 v146, v80, s5, v81
	v_max3_f32 v146, v146, v82, v83
	v_max3_f32 v146, v146, v84, v85
	v_max3_f32 v146, v146, v86, v87
	v_max3_f32 v146, v146, v88, v89
	v_max3_f32 v146, v146, v90, v91
	v_max3_f32 v146, v146, v92, v93
	v_max3_f32 v146, v146, v94, v95
	v_mfma_f32_32x32x16_bf16 v[32:47], v[228:231], v[96:99], 0
	v_max3_f32 v146, v146, v64, v65
	v_max3_f32 v146, v146, v66, v67
	v_max3_f32 v146, v146, v68, v69
	v_max3_f32 v146, v146, v70, v71
	v_mfma_f32_32x32x16_bf16 v[32:47], v[232:235], v[100:103], v[32:47]
	v_max3_f32 v146, v146, v72, v73
	v_max3_f32 v146, v146, v74, v75
	v_max3_f32 v146, v146, v76, v77
	v_max3_f32 v146, v146, v78, v79
	ds_bpermute_b32 v147, v170, v146
	ds_read2_b64 v[220:223], v236 offset0:8 offset1:10
	ds_read2_b64 v[224:227], v237 offset0:40 offset1:42
	ds_read2_b64 v[228:231], v236 offset0:12 offset1:14
	ds_read2_b64 v[232:235], v237 offset0:44 offset1:46
	s_waitcnt lgkmcnt(4)
	v_max_f32_e32 v147, v147, v147
	v_max_f32_e32 v146, v146, v147
	v_mul_f32_e32 v147, 0x3e8293ee, v146
	v_add_f32_e32 v146, 0x41000000, v140
	v_cmp_gt_f32_e32 vcc, v147, v146
	s_cbranch_vccz .Laa_nra
	v_max_f32_e32 v146, v147, v147
	v_max_f32_e32 v147, v140, v140
	v_max_f32_e32 v147, v147, v146
	v_sub_f32_e32 v140, v140, v147
	v_exp_f32_e32 v140, v140
	v_add_f32_e32 v146, 0x41000000, v147
	v_pk_mul_f32 v[18:19], v[18:19], v[140:141] op_sel_hi:[1,0]
	v_pk_mul_f32 v[20:21], v[20:21], v[140:141] op_sel_hi:[1,0]
	v_pk_mul_f32 v[22:23], v[22:23], v[140:141] op_sel_hi:[1,0]
	v_pk_mul_f32 v[24:25], v[24:25], v[140:141] op_sel_hi:[1,0]
	v_pk_mul_f32 v[26:27], v[26:27], v[140:141] op_sel_hi:[1,0]
	v_pk_mul_f32 v[28:29], v[28:29], v[140:141] op_sel_hi:[1,0]
	v_pk_mul_f32 v[16:17], v[16:17], v[140:141] op_sel_hi:[1,0]
	v_pk_mul_f32 v[30:31], v[30:31], v[140:141] op_sel_hi:[1,0]
	v_pk_mul_f32 v[0:1], v[0:1], v[140:141] op_sel_hi:[1,0]
	v_pk_mul_f32 v[2:3], v[2:3], v[140:141] op_sel_hi:[1,0]
	v_pk_mul_f32 v[4:5], v[4:5], v[140:141] op_sel_hi:[1,0]
	v_pk_mul_f32 v[6:7], v[6:7], v[140:141] op_sel_hi:[1,0]
	v_pk_mul_f32 v[8:9], v[8:9], v[140:141] op_sel_hi:[1,0]
	v_pk_mul_f32 v[10:11], v[10:11], v[140:141] op_sel_hi:[1,0]
	v_pk_mul_f32 v[12:13], v[12:13], v[140:141] op_sel_hi:[1,0]
	v_pk_mul_f32 v[14:15], v[14:15], v[140:141] op_sel_hi:[1,0]
	v_mul_f32_e32 v200, v200, v140
	v_mov_b32_e32 v140, v147
; DI unsigned pk2(float a, float b) { hwf32x2 f = {a, b}; hwbf16x2 r = __builtin_convertvector(f, hwbf16x2); return __builtin_bit_cast(unsigned, r); }
; #define MFMA32(a, b, c) __builtin_amdgcn_mfma_f32_32x32x16_bf16((a), (b), (c), 0, 0, 0)
; template <int MODE>
; DI void attn_mfma(const Params& p, int l, int b, int hd, int qb, unsigned char* smem) {
;     ...
;     float mx = -1e30f;
; #pragma unroll
;     for (int mt = 0; mt < 2; ++mt)
; #pragma unroll
;       for (int i = 0; i < 16; ++i) mx = fmaxf(mx, S[mt][i]);
;     mx = fmaxf(mx, __shfl_xor(mx, 32));
;     const float zmx = mx * cexp;
;     if (__any(zmx > mrun + 8.f)) {
;       const float mnew = fmaxf(mrun, zmx);
;       const float alpha = __builtin_amdgcn_exp2f(mrun - mnew);
;     ...
;     const f32x2 c2 = {cexp, cexp}, m2 = {mrun, mrun};
;     f32x2 ps2 = {0.f, 0.f};
;     unsigned pk[2][8];
; #pragma unroll
;     for (int mt = 0; mt < 2; ++mt)
; #pragma unroll
;       for (int i = 0; i < 8; ++i) {
;         f32x2 z = {S[mt][2 * i], S[mt][2 * i + 1]};
;         z = z * c2 - m2;
;         f32x2 pv = {__builtin_amdgcn_exp2f(z.x), __builtin_amdgcn_exp2f(z.y)};
;         ps2 = ps2 + pv;
;         pk[mt][i] = pk2(pv.x, pv.y);
;       }
;     lsum += ps2.x + ps2.y;
; #pragma unroll
;     for (int mt = 0; mt < 2; ++mt)
; #pragma unroll
;       for (int s = 0; s < 2; ++s) {
;         const uint4 pu = make_uint4(pk[mt][4 * s], pk[mt][4 * s + 1], pk[mt][4 * s + 2], pk[mt][4 * s + 3]);
;         const bf16x8 pf = __builtin_bit_cast(bf16x8, pu);
; #pragma unroll
;         for (int vt = 0; vt < 2; ++vt) {
;           const unsigned char* bp = sVc + (vt * 32 + r) * 136 + (mt * 32 + 16 * s + 4 * h2) * 2;
;           const uint2 lo = *(const uint2*)(bp);
;           const uint2 hi = *(const uint2*)(bp + 16);
;           const uint4 u = make_uint4(lo.x, lo.y, hi.x, hi.y);
;           O[vt] = MFMA32(__builtin_bit_cast(bf16x8, u), pf, O[vt]);
;         }
;       }
.Laa_nra:
	v_fma_f32 v80, v80, s8, -v140
	v_fma_f32 v81, v81, s8, -v140
	v_fma_f32 v82, v82, s8, -v140
	v_fma_f32 v83, v83, s8, -v140
	v_fma_f32 v84, v84, s8, -v140
	v_fma_f32 v85, v85, s8, -v140
	v_fma_f32 v86, v86, s8, -v140
	v_fma_f32 v87, v87, s8, -v140
	v_exp_f32_e32 v80, v80
	v_exp_f32_e32 v81, v81
	v_exp_f32_e32 v82, v82
	v_exp_f32_e32 v83, v83
	v_exp_f32_e32 v84, v84
	v_exp_f32_e32 v85, v85
	v_exp_f32_e32 v86, v86
	v_exp_f32_e32 v87, v87
	v_add_f32_e64 v148, v80, 0
	v_add_f32_e64 v149, v81, 0
	v_add_f32_e32 v148, v82, v148
	v_add_f32_e32 v149, v83, v149
	v_add_f32_e32 v148, v84, v148
	v_add_f32_e32 v149, v85, v149
	v_add_f32_e32 v148, v86, v148
	v_add_f32_e32 v149, v87, v149
	v_cvt_pk_bf16_f32 v80, v80, v81
	v_cvt_pk_bf16_f32 v81, v82, v83
	v_cvt_pk_bf16_f32 v82, v84, v85
	v_cvt_pk_bf16_f32 v83, v86, v87
	v_fma_f32 v88, v88, s8, -v140
	v_fma_f32 v89, v89, s8, -v140
	v_fma_f32 v90, v90, s8, -v140
	v_mfma_f32_32x32x16_bf16 v[16:31], v[204:207], v[80:83], v[16:31]
	v_fma_f32 v91, v91, s8, -v140
	v_fma_f32 v92, v92, s8, -v140
	v_fma_f32 v93, v93, s8, -v140
	v_fma_f32 v94, v94, s8, -v140
	v_fma_f32 v95, v95, s8, -v140
	v_exp_f32_e32 v88, v88
	v_exp_f32_e32 v89, v89
	v_exp_f32_e32 v90, v90
	v_exp_f32_e32 v91, v91
	v_exp_f32_e32 v92, v92
	v_exp_f32_e32 v93, v93
	v_exp_f32_e32 v94, v94
	v_mfma_f32_32x32x16_bf16 v[0:15], v[208:211], v[80:83], v[0:15]
	v_exp_f32_e32 v95, v95
	v_add_f32_e32 v148, v88, v148
	v_add_f32_e32 v149, v89, v149
	v_add_f32_e32 v148, v90, v148
	v_add_f32_e32 v149, v91, v149
	v_add_f32_e32 v148, v92, v148
	v_add_f32_e32 v149, v93, v149
	v_add_f32_e32 v148, v94, v148
	v_add_f32_e32 v149, v95, v149
	v_cvt_pk_bf16_f32 v88, v88, v89
	v_cvt_pk_bf16_f32 v89, v90, v91
	v_cvt_pk_bf16_f32 v90, v92, v93
	v_cvt_pk_bf16_f32 v91, v94, v95
	v_fma_f32 v64, v64, s8, -v140
	v_fma_f32 v65, v65, s8, -v140
	v_fma_f32 v66, v66, s8, -v140
	v_mfma_f32_32x32x16_bf16 v[16:31], v[212:215], v[88:91], v[16:31]
	v_fma_f32 v67, v67, s8, -v140
	v_fma_f32 v68, v68, s8, -v140
	v_fma_f32 v69, v69, s8, -v140
	v_fma_f32 v70, v70, s8, -v140
	v_fma_f32 v71, v71, s8, -v140
	v_exp_f32_e32 v64, v64
	v_exp_f32_e32 v65, v65
	v_exp_f32_e32 v66, v66
	v_exp_f32_e32 v67, v67
	v_exp_f32_e32 v68, v68
	v_exp_f32_e32 v69, v69
	v_exp_f32_e32 v70, v70
	v_mfma_f32_32x32x16_bf16 v[0:15], v[216:219], v[88:91], v[0:15]
	v_exp_f32_e32 v71, v71
	v_add_f32_e32 v148, v64, v148
	v_add_f32_e32 v149, v65, v149
	v_add_f32_e32 v148, v66, v148
	v_add_f32_e32 v149, v67, v149
	v_add_f32_e32 v148, v68, v148
	v_add_f32_e32 v149, v69, v149
	v_add_f32_e32 v148, v70, v148
	v_add_f32_e32 v149, v71, v149
	v_cvt_pk_bf16_f32 v84, v64, v65
	v_cvt_pk_bf16_f32 v85, v66, v67
	v_cvt_pk_bf16_f32 v86, v68, v69
	v_cvt_pk_bf16_f32 v87, v70, v71
	v_fma_f32 v72, v72, s8, -v140
	v_fma_f32 v73, v73, s8, -v140
	v_fma_f32 v74, v74, s8, -v140
	s_waitcnt lgkmcnt(0)
	v_mfma_f32_32x32x16_bf16 v[16:31], v[220:223], v[84:87], v[16:31]
	v_fma_f32 v75, v75, s8, -v140
	v_fma_f32 v76, v76, s8, -v140
	v_fma_f32 v77, v77, s8, -v140
	v_fma_f32 v78, v78, s8, -v140
	v_fma_f32 v79, v79, s8, -v140
	v_exp_f32_e32 v72, v72
	v_exp_f32_e32 v73, v73
	v_exp_f32_e32 v74, v74
	v_exp_f32_e32 v75, v75
	v_exp_f32_e32 v76, v76
	v_exp_f32_e32 v77, v77
	v_exp_f32_e32 v78, v78
	v_mfma_f32_32x32x16_bf16 v[0:15], v[224:227], v[84:87], v[0:15]
	v_exp_f32_e32 v79, v79
	v_add_f32_e32 v148, v72, v148
	v_add_f32_e32 v149, v73, v149
	v_add_f32_e32 v148, v74, v148
	v_add_f32_e32 v149, v75, v149
	v_add_f32_e32 v148, v76, v148
	v_add_f32_e32 v149, v77, v149
	v_add_f32_e32 v148, v78, v148
	v_add_f32_e32 v149, v79, v149
	v_cvt_pk_bf16_f32 v64, v72, v73
	v_cvt_pk_bf16_f32 v65, v74, v75
	v_cvt_pk_bf16_f32 v66, v76, v77
	v_cvt_pk_bf16_f32 v67, v78, v79
	v_add_f32_e32 v151, v148, v149
	v_add_f32_e32 v152, v200, v151
	v_mfma_f32_32x32x16_bf16 v[16:31], v[228:231], v[64:67], v[16:31]
	v_max3_f32 v150, v48, s5, v49
	v_max3_f32 v150, v150, v50, v51
	v_max3_f32 v150, v150, v52, v53
	v_max3_f32 v150, v150, v54, v55
	v_max3_f32 v150, v150, v56, v57
	v_max3_f32 v150, v150, v58, v59
	v_max3_f32 v150, v150, v60, v61
	v_max3_f32 v150, v150, v62, v63
	v_mfma_f32_32x32x16_bf16 v[0:15], v[232:235], v[64:67], v[0:15]
	v_max3_f32 v150, v150, v32, v33
	v_max3_f32 v150, v150, v34, v35
	v_max3_f32 v150, v150, v36, v37
	v_max3_f32 v150, v150, v38, v39
	v_max3_f32 v150, v150, v40, v41
	v_max3_f32 v150, v150, v42, v43
	v_max3_f32 v150, v150, v44, v45
	v_max3_f32 v150, v150, v46, v47
	ds_bpermute_b32 v151, v170, v150
	ds_read2_b64 v[204:207], v238 offset0:64 offset1:66
	ds_read2_b64 v[208:211], v239 offset0:96 offset1:98
	ds_read2_b64 v[212:215], v238 offset0:68 offset1:70
	ds_read2_b64 v[216:219], v239 offset0:100 offset1:102
	ds_read2_b64 v[220:223], v238 offset0:72 offset1:74
	ds_read2_b64 v[224:227], v239 offset0:104 offset1:106
	ds_read2_b64 v[228:231], v238 offset0:76 offset1:78
	ds_read2_b64 v[232:235], v239 offset0:108 offset1:110
	s_waitcnt lgkmcnt(8)
	v_max_f32_e32 v151, v151, v151
	v_max_f32_e32 v150, v150, v151
	v_mul_f32_e32 v150, 0x3e8293ee, v150
	v_cmp_gt_f32_e32 vcc, v150, v146
	s_cbranch_vccz .Laa_nrb
	v_max_f32_e32 v150, v150, v150
	v_max_f32_e32 v151, v140, v140
	v_max_f32_e32 v150, v151, v150
	v_sub_f32_e32 v151, v140, v150
	v_exp_f32_e32 v154, v151
	v_mov_b32_e32 v140, v150
	v_pk_mul_f32 v[16:17], v[16:17], v[154:155] op_sel_hi:[1,0]
	v_pk_mul_f32 v[18:19], v[18:19], v[154:155] op_sel_hi:[1,0]
	v_pk_mul_f32 v[20:21], v[20:21], v[154:155] op_sel_hi:[1,0]
	v_pk_mul_f32 v[22:23], v[22:23], v[154:155] op_sel_hi:[1,0]
	v_pk_mul_f32 v[24:25], v[24:25], v[154:155] op_sel_hi:[1,0]
	v_pk_mul_f32 v[26:27], v[26:27], v[154:155] op_sel_hi:[1,0]
	v_pk_mul_f32 v[28:29], v[28:29], v[154:155] op_sel_hi:[1,0]
	v_pk_mul_f32 v[30:31], v[30:31], v[154:155] op_sel_hi:[1,0]
	v_pk_mul_f32 v[0:1], v[0:1], v[154:155] op_sel_hi:[1,0]
	v_pk_mul_f32 v[2:3], v[2:3], v[154:155] op_sel_hi:[1,0]
	v_pk_mul_f32 v[4:5], v[4:5], v[154:155] op_sel_hi:[1,0]
	v_pk_mul_f32 v[6:7], v[6:7], v[154:155] op_sel_hi:[1,0]
	v_pk_mul_f32 v[8:9], v[8:9], v[154:155] op_sel_hi:[1,0]
	v_pk_mul_f32 v[10:11], v[10:11], v[154:155] op_sel_hi:[1,0]
	v_pk_mul_f32 v[12:13], v[12:13], v[154:155] op_sel_hi:[1,0]
	v_pk_mul_f32 v[14:15], v[14:15], v[154:155] op_sel_hi:[1,0]
	v_mul_f32_e32 v152, v152, v154
; DI unsigned pk2(float a, float b) { hwf32x2 f = {a, b}; hwbf16x2 r = __builtin_convertvector(f, hwbf16x2); return __builtin_bit_cast(unsigned, r); }
; #define MFMA32(a, b, c) __builtin_amdgcn_mfma_f32_32x32x16_bf16((a), (b), (c), 0, 0, 0)
; template <int MODE>
; DI void attn_mfma(const Params& p, int l, int b, int hd, int qb, unsigned char* smem) {
;     ...
;     const f32x2 c2 = {cexp, cexp}, m2 = {mrun, mrun};
;     f32x2 ps2 = {0.f, 0.f};
;     unsigned pk[2][8];
; #pragma unroll
;     for (int mt = 0; mt < 2; ++mt)
; #pragma unroll
;       for (int i = 0; i < 8; ++i) {
;         f32x2 z = {S[mt][2 * i], S[mt][2 * i + 1]};
;         z = z * c2 - m2;
;         f32x2 pv = {__builtin_amdgcn_exp2f(z.x), __builtin_amdgcn_exp2f(z.y)};
;         ps2 = ps2 + pv;
;         pk[mt][i] = pk2(pv.x, pv.y);
;       }
;     lsum += ps2.x + ps2.y;
; #pragma unroll
;     for (int mt = 0; mt < 2; ++mt)
; #pragma unroll
;       for (int s = 0; s < 2; ++s) {
;         const uint4 pu = make_uint4(pk[mt][4 * s], pk[mt][4 * s + 1], pk[mt][4 * s + 2], pk[mt][4 * s + 3]);
;         const bf16x8 pf = __builtin_bit_cast(bf16x8, pu);
; #pragma unroll
;         for (int vt = 0; vt < 2; ++vt) {
;           const unsigned char* bp = sVc + (vt * 32 + r) * 136 + (mt * 32 + 16 * s + 4 * h2) * 2;
;           const uint2 lo = *(const uint2*)(bp);
;           const uint2 hi = *(const uint2*)(bp + 16);
;           const uint4 u = make_uint4(lo.x, lo.y, hi.x, hi.y);
;           O[vt] = MFMA32(__builtin_bit_cast(bf16x8, u), pf, O[vt]);
;         }
;       }
;     }
;   }
.Laa_nrb:
	v_fma_f32 v48, v48, s8, -v140
	v_fma_f32 v49, v49, s8, -v140
	v_fma_f32 v50, v50, s8, -v140
	v_fma_f32 v51, v51, s8, -v140
	v_fma_f32 v52, v52, s8, -v140
	v_fma_f32 v53, v53, s8, -v140
	v_fma_f32 v54, v54, s8, -v140
	v_fma_f32 v55, v55, s8, -v140
	v_exp_f32_e32 v48, v48
	v_exp_f32_e32 v49, v49
	v_exp_f32_e32 v50, v50
	v_exp_f32_e32 v51, v51
	v_exp_f32_e32 v52, v52
	v_exp_f32_e32 v53, v53
	v_exp_f32_e32 v54, v54
	v_exp_f32_e32 v55, v55
	v_add_f32_e64 v148, v48, 0
	v_add_f32_e64 v149, v49, 0
	v_add_f32_e32 v148, v50, v148
	v_add_f32_e32 v149, v51, v149
	v_add_f32_e32 v148, v52, v148
	v_add_f32_e32 v149, v53, v149
	v_add_f32_e32 v148, v54, v148
	v_add_f32_e32 v149, v55, v149
	v_cvt_pk_bf16_f32 v48, v48, v49
	v_cvt_pk_bf16_f32 v49, v50, v51
	v_cvt_pk_bf16_f32 v50, v52, v53
	v_cvt_pk_bf16_f32 v51, v54, v55
	v_fma_f32 v56, v56, s8, -v140
	v_fma_f32 v57, v57, s8, -v140
	v_fma_f32 v58, v58, s8, -v140
	s_waitcnt lgkmcnt(4)
	v_mfma_f32_32x32x16_bf16 v[16:31], v[204:207], v[48:51], v[16:31]
	v_fma_f32 v59, v59, s8, -v140
	v_fma_f32 v60, v60, s8, -v140
	v_fma_f32 v61, v61, s8, -v140
	v_fma_f32 v62, v62, s8, -v140
	v_fma_f32 v63, v63, s8, -v140
	v_exp_f32_e32 v56, v56
	v_exp_f32_e32 v57, v57
	v_exp_f32_e32 v58, v58
	v_exp_f32_e32 v59, v59
	v_exp_f32_e32 v60, v60
	v_exp_f32_e32 v61, v61
	v_exp_f32_e32 v62, v62
	v_mfma_f32_32x32x16_bf16 v[0:15], v[208:211], v[48:51], v[0:15]
	v_exp_f32_e32 v63, v63
	v_add_f32_e32 v148, v56, v148
	v_add_f32_e32 v149, v57, v149
	v_add_f32_e32 v148, v58, v148
	v_add_f32_e32 v149, v59, v149
	v_add_f32_e32 v148, v60, v148
	v_add_f32_e32 v149, v61, v149
	v_add_f32_e32 v148, v62, v148
	v_add_f32_e32 v149, v63, v149
	v_cvt_pk_bf16_f32 v56, v56, v57
	v_cvt_pk_bf16_f32 v57, v58, v59
	v_cvt_pk_bf16_f32 v58, v60, v61
	v_cvt_pk_bf16_f32 v59, v62, v63
	v_fma_f32 v32, v32, s8, -v140
	v_fma_f32 v33, v33, s8, -v140
	v_fma_f32 v34, v34, s8, -v140
	v_mfma_f32_32x32x16_bf16 v[16:31], v[212:215], v[56:59], v[16:31]
	v_fma_f32 v35, v35, s8, -v140
	v_fma_f32 v36, v36, s8, -v140
	v_fma_f32 v37, v37, s8, -v140
	v_fma_f32 v38, v38, s8, -v140
	v_fma_f32 v39, v39, s8, -v140
	v_exp_f32_e32 v32, v32
	v_exp_f32_e32 v33, v33
	v_exp_f32_e32 v34, v34
	v_exp_f32_e32 v35, v35
	v_exp_f32_e32 v36, v36
	v_exp_f32_e32 v37, v37
	v_exp_f32_e32 v38, v38
	v_mfma_f32_32x32x16_bf16 v[0:15], v[216:219], v[56:59], v[0:15]
	v_exp_f32_e32 v39, v39
	v_add_f32_e32 v148, v32, v148
	v_add_f32_e32 v149, v33, v149
	v_add_f32_e32 v148, v34, v148
	v_add_f32_e32 v149, v35, v149
	v_add_f32_e32 v148, v36, v148
	v_add_f32_e32 v149, v37, v149
	v_add_f32_e32 v148, v38, v148
	v_add_f32_e32 v149, v39, v149
	v_cvt_pk_bf16_f32 v52, v32, v33
	v_cvt_pk_bf16_f32 v53, v34, v35
	v_cvt_pk_bf16_f32 v54, v36, v37
	v_cvt_pk_bf16_f32 v55, v38, v39
	v_fma_f32 v40, v40, s8, -v140
	v_fma_f32 v41, v41, s8, -v140
	v_fma_f32 v42, v42, s8, -v140
	s_waitcnt lgkmcnt(0)
	v_mfma_f32_32x32x16_bf16 v[16:31], v[220:223], v[52:55], v[16:31]
	v_fma_f32 v43, v43, s8, -v140
	v_fma_f32 v44, v44, s8, -v140
	v_fma_f32 v45, v45, s8, -v140
	v_fma_f32 v46, v46, s8, -v140
	v_fma_f32 v47, v47, s8, -v140
	v_exp_f32_e32 v40, v40
	v_exp_f32_e32 v41, v41
	v_exp_f32_e32 v42, v42
	v_exp_f32_e32 v43, v43
	v_exp_f32_e32 v44, v44
	v_exp_f32_e32 v45, v45
	v_exp_f32_e32 v46, v46
	v_mfma_f32_32x32x16_bf16 v[0:15], v[224:227], v[52:55], v[0:15]
	v_exp_f32_e32 v47, v47
	v_add_f32_e32 v148, v40, v148
	v_add_f32_e32 v149, v41, v149
	v_add_f32_e32 v148, v42, v148
	v_add_f32_e32 v149, v43, v149
	v_add_f32_e32 v148, v44, v148
	v_add_f32_e32 v149, v45, v149
	v_add_f32_e32 v148, v46, v148
	v_add_f32_e32 v149, v47, v149
	v_cvt_pk_bf16_f32 v32, v40, v41
	v_cvt_pk_bf16_f32 v33, v42, v43
	v_cvt_pk_bf16_f32 v34, v44, v45
	v_cvt_pk_bf16_f32 v35, v46, v47
	v_add_f32_e32 v151, v148, v149
	v_add_f32_e32 v200, v152, v151
	v_mfma_f32_32x32x16_bf16 v[16:31], v[228:231], v[32:35], v[16:31]
	s_mov_b64 s[8:9], 0x100
	v_lshl_add_u64 v[136:137], v[136:137], 0, s[8:9]
	s_mov_b64 s[8:9], 0x111000
	v_lshl_add_u64 v[138:139], v[138:139], 0, s[8:9]
	v_mfma_f32_32x32x16_bf16 v[0:15], v[232:235], v[32:35], v[0:15]
	s_and_b64 vcc, exec, s[0:1]
	s_cbranch_vccz .LBB0_580
